# attention unit epilogues: counted vmcnt waits (each gain vector waited for only where it is first used)
# baseline (speedup 1.0000x reference)
.LBB0_936:
	s_or_b64 exec, exec, s[2:3]
	s_waitcnt lgkmcnt(0)
	s_barrier
	s_and_saveexec_b64 s[2:3], s[6:7]
	s_cbranch_execz .LBB0_939
	v_lshlrev_b64 v[48:49], 11, v[0:1]
	v_lshl_add_u64 v[48:49], s[8:9], 0, v[48:49]
	s_lshl_b32 s10, s35, 7
	v_lshl_add_u64 v[56:57], v[48:49], 0, s[10:11]
	s_lshl_b32 s10, s35, 8
	v_lshl_add_u64 v[58:59], v[162:163], 0, s[10:11]
	ds_read2_b32 v[42:43], v204 offset1:1
	ds_read2_b32 v[40:41], v204 offset0:2 offset1:3
	ds_read2_b32 v[44:45], v204 offset0:4 offset1:5
	ds_read2_b32 v[46:47], v204 offset0:6 offset1:7
	global_load_dwordx4 v[48:51], v[58:59], off
	global_load_dwordx4 v[52:55], v[58:59], off offset:128
	global_load_dwordx4 v[108:111], v[58:59], off offset:32
	global_load_dwordx4 v[112:115], v[58:59], off offset:160
	global_load_dwordx4 v[116:119], v[58:59], off offset:64
	global_load_dwordx4 v[120:123], v[58:59], off offset:192
	global_load_dwordx4 v[124:127], v[58:59], off offset:96
	global_load_dwordx4 v[128:131], v[58:59], off offset:224
	v_max_f32_e32 v34, v95, v95
	s_waitcnt lgkmcnt(3)
	v_max_f32_e32 v35, v42, v42
	v_max_f32_e32 v35, v34, v35
	v_sub_f32_e32 v34, v95, v35
	v_sub_f32_e32 v35, v42, v35
	v_exp_f32_e32 v34, v34
	v_exp_f32_e32 v37, v35
	s_waitcnt lgkmcnt(1)
	v_mov_b32_e32 v35, v44
	v_mov_b32_e32 v36, v20
	v_mov_b32_e32 v42, v34
	v_mov_b32_e32 v39, v37
	v_pk_mul_f32 v[38:39], v[38:39], v[42:43]
	v_pk_mul_f32 v[60:61], v[36:37], v[34:35]
	v_add_f32_e32 v20, v38, v39
	v_div_scale_f32 v36, s[48:49], v20, v20, 1.0
	v_rcp_f32_e32 v42, v36
	v_mov_b32_e32 v35, v45
	v_add_f32_e32 v44, v60, v61
	ds_read2_b32 v[38:39], v204 offset0:20 offset1:21
	v_fma_f32 v43, -v36, v42, 1.0
	v_fmac_f32_e32 v42, v43, v42
	v_div_scale_f32 v43, vcc, 1.0, v20, 1.0
	v_mul_f32_e32 v45, v43, v42
	v_fma_f32 v60, -v36, v45, v43
	v_fmac_f32_e32 v45, v60, v42
	v_fma_f32 v36, -v36, v45, v43
	v_div_fmas_f32 v36, v36, v42, v45
	v_div_fixup_f32 v76, v36, v20, 1.0
	v_mov_b32_e32 v42, v34
	v_mov_b32_e32 v43, v40
	v_mov_b32_e32 v36, v18
	v_pk_mul_f32 v[42:43], v[36:37], v[42:43]
	v_mov_b32_e32 v40, v34
	v_add_f32_e32 v18, v42, v43
	v_mov_b32_e32 v36, v19
	v_mul_f32_e32 v77, v18, v76
	v_pk_mul_f32 v[18:19], v[36:37], v[40:41]
	ds_read2_b32 v[40:41], v204 offset0:18 offset1:19
	ds_read2_b32 v[42:43], v204 offset0:22 offset1:23
	v_add_f32_e32 v18, v18, v19
	v_mul_f32_e32 v78, v76, v18
	v_mov_b32_e32 v18, v34
	s_waitcnt lgkmcnt(2)
	v_mov_b32_e32 v19, v38
	v_mov_b32_e32 v36, v4
	v_pk_mul_f32 v[18:19], v[36:37], v[18:19]
	v_mov_b32_e32 v36, v21
	v_add_f32_e32 v4, v18, v19
	v_pk_mul_f32 v[18:19], v[36:37], v[34:35]
	v_mul_f32_e32 v80, v76, v4
	v_add_f32_e32 v4, v18, v19
	v_mov_b32_e32 v18, v34
	s_waitcnt lgkmcnt(1)
	v_mov_b32_e32 v19, v40
	v_mov_b32_e32 v36, v2
	v_pk_mul_f32 v[18:19], v[36:37], v[18:19]
	v_mov_b32_e32 v40, v34
	v_add_f32_e32 v2, v18, v19
	v_mov_b32_e32 v36, v3
	v_mul_f32_e32 v82, v2, v76
	v_pk_mul_f32 v[2:3], v[36:37], v[40:41]
	v_mov_b32_e32 v35, v39
	v_add_f32_e32 v2, v2, v3
	v_mov_b32_e32 v36, v5
	v_mul_f32_e32 v83, v76, v2
	v_pk_mul_f32 v[2:3], v[36:37], v[34:35]
	v_mul_f32_e32 v79, v76, v44
	v_add_f32_e32 v2, v2, v3
	v_mul_f32_e32 v81, v76, v4
	ds_read2_b32 v[44:45], v204 offset0:16 offset1:17
	v_mul_f32_e32 v84, v76, v2
	ds_read2_b32 v[4:5], v204 offset0:8 offset1:9
	ds_read2_b32 v[60:61], v204 offset0:10 offset1:11
	ds_read2_b32 v[62:63], v204 offset0:12 offset1:13
	ds_read2_b32 v[64:65], v204 offset0:14 offset1:15
	ds_read2_b32 v[66:67], v204 offset0:24 offset1:25
	ds_read2_b32 v[68:69], v204 offset0:26 offset1:27
	ds_read2_b32 v[70:71], v204 offset0:28 offset1:29
	ds_read2_b32 v[72:73], v204 offset0:30 offset1:31
	ds_read2_b32 v[74:75], v204 offset0:32 offset1:33
	v_lshlrev_b32_e32 v2, 1, v197
	v_mov_b32_e32 v3, v1
	v_lshl_add_u64 v[2:3], v[56:57], 0, v[2:3]
	s_waitcnt lgkmcnt(8)
	v_mov_b32_e32 v35, v4
	v_mov_b32_e32 v36, v24
	v_mul_f32_e32 v56, v83, v83
	v_fmac_f32_e32 v56, v78, v78
	s_waitcnt vmcnt(7)
	v_mul_f32_e32 v18, v77, v48
	v_mul_f32_e32 v19, v78, v49
	v_cvt_pk_bf16_f32 v18, v18, v19
	v_mul_f32_e32 v19, v79, v50
	v_mul_f32_e32 v20, v81, v51
	v_cvt_pk_bf16_f32 v19, v19, v20
	global_store_dwordx2 v[2:3], v[18:19], off
	s_waitcnt vmcnt(7)
	v_mul_f32_e32 v18, v82, v52
	v_mul_f32_e32 v19, v83, v53
	v_cvt_pk_bf16_f32 v18, v18, v19
	v_mul_f32_e32 v19, v80, v54
	v_mul_f32_e32 v20, v84, v55
	v_cvt_pk_bf16_f32 v19, v19, v20
	global_store_dwordx2 v[2:3], v[18:19], off offset:64
	s_waitcnt vmcnt(6)
	v_mov_b32_e32 v18, v108
	v_mov_b32_e32 v19, v109
	v_mov_b32_e32 v20, v110
	v_mov_b32_e32 v21, v111
	s_nop 0
	v_mov_b32_e32 v38, v112
	v_mov_b32_e32 v39, v113
	v_mov_b32_e32 v40, v114
	v_mov_b32_e32 v41, v115
	v_mov_b32_e32 v49, v46
	v_mov_b32_e32 v48, v34
	v_pk_mul_f32 v[54:55], v[36:37], v[34:35]
	v_mov_b32_e32 v36, v22
	v_mov_b32_e32 v46, v34
	v_mov_b32_e32 v35, v5
	v_pk_mul_f32 v[4:5], v[36:37], v[48:49]
	v_mov_b32_e32 v36, v23
	s_waitcnt lgkmcnt(4)
	v_mov_b32_e32 v51, v66
	v_mov_b32_e32 v50, v34
	v_add_f32_e32 v23, v4, v5
	v_pk_mul_f32 v[4:5], v[36:37], v[46:47]
	v_mov_b32_e32 v36, v8
	v_add_f32_e32 v8, v4, v5
	v_pk_mul_f32 v[4:5], v[36:37], v[50:51]
	v_mov_b32_e32 v36, v25
	v_mov_b32_e32 v53, v42
	v_mov_b32_e32 v52, v34
	v_add_f32_e32 v24, v4, v5
	v_pk_mul_f32 v[4:5], v[36:37], v[34:35]
	v_mov_b32_e32 v36, v6
	v_mov_b32_e32 v42, v34
	v_add_f32_e32 v6, v4, v5
	v_pk_mul_f32 v[4:5], v[36:37], v[52:53]
	v_mov_b32_e32 v36, v7
	v_mov_b32_e32 v35, v67
	v_add_f32_e32 v7, v4, v5
	v_pk_mul_f32 v[4:5], v[36:37], v[42:43]
	v_mov_b32_e32 v36, v9
	v_add_f32_e32 v9, v4, v5
	v_pk_mul_f32 v[4:5], v[36:37], v[34:35]
	v_add_f32_e32 v22, v54, v55
	v_mul_f32_e32 v49, v76, v23
	v_mul_f32_e32 v50, v76, v8
	v_add_f32_e32 v4, v4, v5
	v_mul_f32_e32 v48, v76, v22
	v_mul_f32_e32 v52, v76, v6
	v_mul_f32_e32 v55, v76, v4
	v_mul_f32_e32 v51, v76, v24
	v_mul_f32_e32 v53, v76, v7
	v_mul_f32_e32 v54, v76, v9
	v_mov_b32_e32 v35, v62
	v_mov_b32_e32 v36, v28
	v_pk_mul_f32 v[46:47], v[36:37], v[34:35]
	v_mov_b32_e32 v36, v26
	v_add_f32_e32 v46, v46, v47
	s_waitcnt lgkmcnt(2)
	v_mov_b32_e32 v23, v70
	v_mov_b32_e32 v22, v34
	v_mov_b32_e32 v35, v63
	v_mov_b32_e32 v25, v68
	v_mov_b32_e32 v24, v34
	v_mov_b32_e32 v68, v34
	v_mul_f32_e32 v28, v82, v82
	v_mul_f32_e32 v26, v80, v80
	v_fmac_f32_e32 v28, v77, v77
	v_mul_f32_e32 v57, v84, v84
	v_fmac_f32_e32 v26, v79, v79
	v_fmac_f32_e32 v57, v81, v81
	s_waitcnt lgkmcnt(1)
	v_mov_b32_e32 v43, v72
	v_mov_b32_e32 v72, v34
	v_mul_f32_e32 v4, v49, v18
	v_mul_f32_e32 v5, v50, v19
	v_mul_f32_e32 v6, v48, v20
	v_mul_f32_e32 v7, v52, v21
	v_cvt_pk_bf16_f32 v4, v4, v5
	v_cvt_pk_bf16_f32 v5, v6, v7
	v_mul_f32_e32 v8, v53, v38
	v_mul_f32_e32 v9, v54, v39
	v_mul_f32_e32 v18, v51, v40
	v_mul_f32_e32 v19, v55, v41
	global_store_dwordx2 v[2:3], v[4:5], off offset:16
	v_cvt_pk_bf16_f32 v4, v8, v9
	v_cvt_pk_bf16_f32 v5, v18, v19
	global_store_dwordx2 v[2:3], v[4:5], off offset:80
	s_waitcnt vmcnt(6)
	v_mov_b32_e32 v4, v116
	v_mov_b32_e32 v5, v117
	v_mov_b32_e32 v6, v118
	v_mov_b32_e32 v7, v119
	s_nop 0
	v_mov_b32_e32 v18, v120
	v_mov_b32_e32 v19, v121
	v_mov_b32_e32 v20, v122
	v_mov_b32_e32 v21, v123
	v_mov_b32_e32 v9, v60
	v_mov_b32_e32 v8, v34
	v_mov_b32_e32 v60, v34
	v_pk_mul_f32 v[8:9], v[36:37], v[8:9]
	v_mov_b32_e32 v36, v27
	v_mul_f32_e32 v27, v76, v46
	v_add_f32_e32 v46, v8, v9
	v_pk_mul_f32 v[8:9], v[36:37], v[60:61]
	v_mov_b32_e32 v36, v12
	v_add_f32_e32 v12, v8, v9
	v_pk_mul_f32 v[8:9], v[36:37], v[22:23]
	v_mov_b32_e32 v36, v29
	v_mul_f32_e32 v22, v76, v12
	v_add_f32_e32 v12, v8, v9
	v_pk_mul_f32 v[8:9], v[36:37], v[34:35]
	v_mov_b32_e32 v36, v10
	v_add_f32_e32 v10, v8, v9
	v_pk_mul_f32 v[8:9], v[36:37], v[24:25]
	v_mov_b32_e32 v36, v11
	v_mov_b32_e32 v35, v71
	v_mul_f32_e32 v24, v76, v10
	v_add_f32_e32 v10, v8, v9
	v_pk_mul_f32 v[8:9], v[36:37], v[68:69]
	v_mov_b32_e32 v36, v13
	v_mul_f32_e32 v46, v76, v46
	v_mul_f32_e32 v25, v76, v10
	v_add_f32_e32 v10, v8, v9
	v_pk_mul_f32 v[8:9], v[36:37], v[34:35]
	v_mul_f32_e32 v23, v76, v12
	v_add_f32_e32 v8, v8, v9
	v_mul_f32_e32 v29, v76, v10
	v_mul_f32_e32 v47, v76, v8
	v_mul_f32_e32 v51, v51, v51
	v_fmac_f32_e32 v51, v48, v48
	v_mov_b32_e32 v35, v44
	v_mov_b32_e32 v36, v32
	v_mov_b32_e32 v39, v64
	v_mov_b32_e32 v38, v34
	v_mov_b32_e32 v64, v34
	s_waitcnt lgkmcnt(0)
	v_mov_b32_e32 v41, v74
	v_mov_b32_e32 v40, v34
	v_mul_f32_e32 v4, v46, v4
	v_mul_f32_e32 v5, v22, v5
	v_mul_f32_e32 v6, v27, v6
	v_mul_f32_e32 v7, v24, v7
	v_cvt_pk_bf16_f32 v4, v4, v5
	v_cvt_pk_bf16_f32 v5, v6, v7
	v_mul_f32_e32 v8, v25, v18
	v_mul_f32_e32 v9, v29, v19
	v_mul_f32_e32 v10, v23, v20
	v_mul_f32_e32 v11, v47, v21
	global_store_dwordx2 v[2:3], v[4:5], off offset:32
	v_cvt_pk_bf16_f32 v4, v8, v9
	v_cvt_pk_bf16_f32 v5, v10, v11
	global_store_dwordx2 v[2:3], v[4:5], off offset:96
	s_waitcnt vmcnt(6)
	v_mov_b32_e32 v6, v124
	v_mov_b32_e32 v7, v125
	v_mov_b32_e32 v8, v126
	v_mov_b32_e32 v9, v127
	v_mov_b32_e32 v10, v128
	v_mov_b32_e32 v11, v129
	v_mov_b32_e32 v12, v130
	v_mov_b32_e32 v13, v131
	v_add_f32_e32 v19, v28, v56
	v_mul_f32_e32 v4, v53, v53
	v_add_f32_e32 v19, v19, v26
	v_mul_f32_e32 v5, v54, v54
	v_fmac_f32_e32 v4, v49, v49
	v_add_f32_e32 v19, v19, v57
	v_fmac_f32_e32 v5, v50, v50
	v_add_f32_e32 v4, v19, v4
	v_mul_f32_e32 v18, v55, v55
	v_add_f32_e32 v4, v4, v5
	v_fmac_f32_e32 v18, v52, v52
	v_add_f32_e32 v20, v4, v51
	v_mul_f32_e32 v21, v25, v25
	v_pk_mul_f32 v[4:5], v[36:37], v[34:35]
	v_mov_b32_e32 v36, v30
	v_mul_f32_e32 v19, v23, v23
	v_add_f32_e32 v18, v20, v18
	v_fmac_f32_e32 v21, v46, v46
	v_mul_f32_e32 v20, v29, v29
	v_add_f32_e32 v23, v4, v5
	v_pk_mul_f32 v[4:5], v[36:37], v[38:39]
	v_mov_b32_e32 v36, v31
	v_add_f32_e32 v18, v18, v21
	v_fmac_f32_e32 v20, v22, v22
	v_mul_f32_e32 v22, v76, v23
	v_add_f32_e32 v23, v4, v5
	v_pk_mul_f32 v[4:5], v[36:37], v[64:65]
	v_mov_b32_e32 v36, v16
	v_fmac_f32_e32 v19, v27, v27
	v_mov_b32_e32 v35, v45
	v_mul_f32_e32 v21, v47, v47
	v_add_f32_e32 v16, v18, v20
	v_add_f32_e32 v20, v4, v5
	v_pk_mul_f32 v[4:5], v[36:37], v[40:41]
	v_mov_b32_e32 v36, v33
	v_fmac_f32_e32 v21, v24, v24
	v_add_f32_e32 v16, v16, v19
	v_mul_f32_e32 v19, v76, v20
	v_add_f32_e32 v20, v4, v5
	v_pk_mul_f32 v[4:5], v[36:37], v[34:35]
	v_mov_b32_e32 v36, v14
	v_add_f32_e32 v14, v16, v21
	v_mul_f32_e32 v16, v76, v20
	v_add_f32_e32 v20, v4, v5
	v_pk_mul_f32 v[4:5], v[36:37], v[42:43]
	v_mov_b32_e32 v36, v15
	v_add_f32_e32 v21, v4, v5
	v_pk_mul_f32 v[4:5], v[36:37], v[72:73]
	v_mov_b32_e32 v35, v75
	v_mov_b32_e32 v36, v17
	v_mul_f32_e32 v17, v76, v21
	v_add_f32_e32 v21, v4, v5
	v_mul_f32_e32 v18, v76, v23
	v_pk_mul_f32 v[4:5], v[36:37], v[34:35]
	v_mul_f32_e32 v23, v17, v17
	v_mul_f32_e32 v21, v76, v21
	v_add_f32_e32 v4, v4, v5
	v_fmac_f32_e32 v23, v18, v18
	v_mul_f32_e32 v5, v21, v21
	v_mul_f32_e32 v15, v16, v16
	v_mul_f32_e32 v24, v76, v4
	v_add_f32_e32 v4, v14, v23
	v_fmac_f32_e32 v5, v19, v19
	v_mul_f32_e32 v20, v76, v20
	v_fmac_f32_e32 v15, v22, v22
	v_mul_f32_e32 v14, v24, v24
	v_add_f32_e32 v4, v4, v5
	v_fmac_f32_e32 v14, v20, v20
	v_add_f32_e32 v4, v4, v15
	v_add_f32_e32 v4, v4, v14
	ds_bpermute_b32 v5, v96, v4
	v_mul_f32_e32 v6, v18, v6
	v_mul_f32_e32 v7, v19, v7
	v_mul_f32_e32 v8, v22, v8
	v_mul_f32_e32 v9, v20, v9
	v_cvt_pk_bf16_f32 v6, v6, v7
	v_cvt_pk_bf16_f32 v7, v8, v9
	v_mul_f32_e32 v10, v17, v10
	v_mul_f32_e32 v11, v21, v11
	v_mul_f32_e32 v12, v16, v12
	v_mul_f32_e32 v13, v24, v13
	global_store_dwordx2 v[2:3], v[6:7], off offset:48
	v_cvt_pk_bf16_f32 v6, v10, v11
	v_cvt_pk_bf16_f32 v7, v12, v13
	global_store_dwordx2 v[2:3], v[6:7], off offset:112
	s_and_b64 exec, exec, s[0:1]
	s_cbranch_execz .LBB0_939
	v_lshlrev_b64 v[2:3], 5, v[0:1]
	v_lshl_add_u64 v[2:3], s[20:21], 0, v[2:3]
	s_lshl_b32 s10, s35, 2
	v_lshl_add_u64 v[2:3], v[2:3], 0, s[10:11]
	s_waitcnt lgkmcnt(0)
	v_add_f32_e32 v0, v4, v5
	global_store_dword v[2:3], v0, off

.LBB0_961:
	s_or_b64 exec, exec, s[2:3]
	s_waitcnt lgkmcnt(0)
	s_barrier
	s_and_saveexec_b64 s[2:3], s[6:7]
	s_cbranch_execz .LBB0_929
	v_lshlrev_b64 v[46:47], 11, v[178:179]
	v_lshl_add_u64 v[46:47], s[8:9], 0, v[46:47]
	s_lshl_b32 s10, s47, 7
	v_lshl_add_u64 v[56:57], v[46:47], 0, s[10:11]
	s_lshl_b32 s10, s47, 8
	v_lshl_add_u64 v[58:59], v[162:163], 0, s[10:11]
	ds_read2_b32 v[40:41], v204 offset1:1
	ds_read2_b32 v[38:39], v204 offset0:2 offset1:3
	ds_read2_b32 v[42:43], v204 offset0:4 offset1:5
	ds_read2_b32 v[44:45], v204 offset0:6 offset1:7
	global_load_dwordx4 v[48:51], v[58:59], off
	global_load_dwordx4 v[52:55], v[58:59], off offset:128
	global_load_dwordx4 v[108:111], v[58:59], off offset:32
	global_load_dwordx4 v[112:115], v[58:59], off offset:160
	global_load_dwordx4 v[116:119], v[58:59], off offset:64
	global_load_dwordx4 v[120:123], v[58:59], off offset:192
	global_load_dwordx4 v[124:127], v[58:59], off offset:96
	global_load_dwordx4 v[128:131], v[58:59], off offset:224
	v_max_f32_e32 v0, v173, v173
	s_waitcnt lgkmcnt(3)
	v_max_f32_e32 v34, v40, v40
	v_max_f32_e32 v0, v0, v34
	v_sub_f32_e32 v34, v173, v0
	v_sub_f32_e32 v0, v40, v0
	v_exp_f32_e32 v34, v34
	v_exp_f32_e32 v47, v0
	v_mov_b32_e32 v46, v20
	s_waitcnt lgkmcnt(1)
	v_mov_b32_e32 v35, v42
	v_mov_b32_e32 v40, v34
	v_mov_b32_e32 v37, v47
	v_pk_mul_f32 v[36:37], v[36:37], v[40:41]
	v_pk_mul_f32 v[60:61], v[46:47], v[34:35]
	v_add_f32_e32 v0, v36, v37
	v_div_scale_f32 v20, s[34:35], v0, v0, 1.0
	v_rcp_f32_e32 v40, v20
	v_mov_b32_e32 v35, v43
	ds_read2_b32 v[36:37], v204 offset0:20 offset1:21
	v_add_f32_e32 v42, v60, v61
	v_fma_f32 v41, -v20, v40, 1.0
	v_fmac_f32_e32 v40, v41, v40
	v_div_scale_f32 v41, vcc, 1.0, v0, 1.0
	v_mul_f32_e32 v43, v41, v40
	v_fma_f32 v46, -v20, v43, v41
	v_fmac_f32_e32 v43, v46, v40
	v_fma_f32 v20, -v20, v43, v41
	v_div_fmas_f32 v20, v20, v40, v43
	v_mov_b32_e32 v40, v34
	v_mov_b32_e32 v41, v38
	v_mov_b32_e32 v46, v18
	v_pk_mul_f32 v[40:41], v[46:47], v[40:41]
	v_mov_b32_e32 v38, v34
	v_mov_b32_e32 v46, v19
	v_div_fixup_f32 v76, v20, v0, 1.0
	v_add_f32_e32 v0, v40, v41
	v_pk_mul_f32 v[18:19], v[46:47], v[38:39]
	ds_read2_b32 v[38:39], v204 offset0:18 offset1:19
	ds_read2_b32 v[40:41], v204 offset0:22 offset1:23
	v_mul_f32_e32 v77, v0, v76
	v_add_f32_e32 v0, v18, v19
	v_mov_b32_e32 v18, v34
	s_waitcnt lgkmcnt(2)
	v_mov_b32_e32 v19, v36
	v_mov_b32_e32 v46, v4
	v_pk_mul_f32 v[18:19], v[46:47], v[18:19]
	v_mov_b32_e32 v46, v21
	v_mul_f32_e32 v78, v76, v0
	v_add_f32_e32 v0, v18, v19
	v_pk_mul_f32 v[18:19], v[46:47], v[34:35]
	v_mul_f32_e32 v80, v76, v0
	v_add_f32_e32 v0, v18, v19
	v_mov_b32_e32 v18, v34
	s_waitcnt lgkmcnt(1)
	v_mov_b32_e32 v19, v38
	v_mov_b32_e32 v46, v2
	v_pk_mul_f32 v[18:19], v[46:47], v[18:19]
	v_mov_b32_e32 v38, v34
	v_mov_b32_e32 v46, v3
	v_mul_f32_e32 v81, v76, v0
	v_mov_b32_e32 v35, v37
	v_add_f32_e32 v0, v18, v19
	v_pk_mul_f32 v[2:3], v[46:47], v[38:39]
	v_mov_b32_e32 v46, v5
	v_mul_f32_e32 v82, v0, v76
	v_add_f32_e32 v0, v2, v3
	v_pk_mul_f32 v[2:3], v[46:47], v[34:35]
	v_mul_f32_e32 v83, v76, v0
	v_add_f32_e32 v0, v2, v3
	v_mul_f32_e32 v84, v76, v0
	v_lshlrev_b32_e32 v0, 1, v197
	v_mul_f32_e32 v79, v76, v42
	v_lshl_add_u64 v[2:3], v[56:57], 0, v[0:1]
	ds_read2_b32 v[42:43], v204 offset0:16 offset1:17
	ds_read2_b32 v[4:5], v204 offset0:8 offset1:9
	ds_read2_b32 v[60:61], v204 offset0:10 offset1:11
	ds_read2_b32 v[62:63], v204 offset0:12 offset1:13
	ds_read2_b32 v[64:65], v204 offset0:14 offset1:15
	ds_read2_b32 v[66:67], v204 offset0:24 offset1:25
	ds_read2_b32 v[68:69], v204 offset0:26 offset1:27
	ds_read2_b32 v[70:71], v204 offset0:28 offset1:29
	ds_read2_b32 v[72:73], v204 offset0:30 offset1:31
	ds_read2_b32 v[74:75], v204 offset0:32 offset1:33
	s_waitcnt lgkmcnt(8)
	v_mov_b32_e32 v35, v4
	v_mov_b32_e32 v46, v24
	v_mov_b32_e32 v24, v34
	v_mul_f32_e32 v56, v84, v84
	v_fmac_f32_e32 v56, v81, v81
	s_waitcnt vmcnt(7)
	v_mul_f32_e32 v0, v77, v48
	v_mul_f32_e32 v18, v78, v49
	v_mul_f32_e32 v19, v81, v51
	v_cvt_pk_bf16_f32 v18, v0, v18
	v_mul_f32_e32 v0, v79, v50
	v_cvt_pk_bf16_f32 v19, v0, v19
	global_store_dwordx2 v[2:3], v[18:19], off
	s_waitcnt vmcnt(7)
	v_mul_f32_e32 v0, v82, v52
	v_mul_f32_e32 v18, v83, v53
	v_mul_f32_e32 v19, v84, v55
	v_cvt_pk_bf16_f32 v18, v0, v18
	v_mul_f32_e32 v0, v80, v54
	v_cvt_pk_bf16_f32 v19, v0, v19
	global_store_dwordx2 v[2:3], v[18:19], off offset:64
	s_waitcnt vmcnt(6)
	v_mov_b32_e32 v18, v108
	v_mov_b32_e32 v19, v109
	v_mov_b32_e32 v20, v110
	v_mov_b32_e32 v21, v111
	s_nop 0
	v_mov_b32_e32 v36, v112
	v_mov_b32_e32 v37, v113
	v_mov_b32_e32 v38, v114
	v_mov_b32_e32 v39, v115
	v_mov_b32_e32 v49, v44
	v_mov_b32_e32 v48, v34
	v_pk_mul_f32 v[54:55], v[46:47], v[34:35]
	v_mov_b32_e32 v46, v22
	v_mov_b32_e32 v44, v34
	v_mov_b32_e32 v35, v5
	v_pk_mul_f32 v[4:5], v[46:47], v[48:49]
	v_mov_b32_e32 v46, v23
	s_waitcnt lgkmcnt(4)
	v_mov_b32_e32 v51, v66
	v_mov_b32_e32 v50, v34
	v_add_f32_e32 v22, v4, v5
	v_pk_mul_f32 v[4:5], v[46:47], v[44:45]
	v_mov_b32_e32 v46, v8
	v_add_f32_e32 v8, v4, v5
	v_pk_mul_f32 v[4:5], v[46:47], v[50:51]
	v_mov_b32_e32 v46, v25
	v_mov_b32_e32 v53, v40
	v_mov_b32_e32 v52, v34
	v_add_f32_e32 v23, v4, v5
	v_pk_mul_f32 v[4:5], v[46:47], v[34:35]
	v_mov_b32_e32 v46, v6
	v_mov_b32_e32 v40, v34
	v_add_f32_e32 v6, v4, v5
	v_pk_mul_f32 v[4:5], v[46:47], v[52:53]
	v_mov_b32_e32 v46, v7
	v_mov_b32_e32 v35, v67
	v_add_f32_e32 v7, v4, v5
	v_pk_mul_f32 v[4:5], v[46:47], v[40:41]
	v_mov_b32_e32 v46, v9
	v_add_f32_e32 v9, v4, v5
	v_pk_mul_f32 v[4:5], v[46:47], v[34:35]
	v_add_f32_e32 v0, v54, v55
	v_mul_f32_e32 v48, v76, v22
	v_mul_f32_e32 v49, v76, v8
	v_add_f32_e32 v4, v4, v5
	v_mul_f32_e32 v0, v76, v0
	v_mul_f32_e32 v51, v76, v6
	v_mul_f32_e32 v54, v76, v4
	v_mul_f32_e32 v50, v76, v23
	v_mul_f32_e32 v52, v76, v7
	v_mul_f32_e32 v53, v76, v9
	v_mov_b32_e32 v35, v62
	v_mov_b32_e32 v46, v28
	v_pk_mul_f32 v[44:45], v[46:47], v[34:35]
	v_mov_b32_e32 v46, v26
	v_add_f32_e32 v44, v44, v45
	s_waitcnt lgkmcnt(2)
	v_mov_b32_e32 v23, v70
	v_mov_b32_e32 v22, v34
	v_mov_b32_e32 v35, v63
	v_mov_b32_e32 v25, v68
	v_mov_b32_e32 v68, v34
	v_mul_f32_e32 v28, v82, v82
	v_mul_f32_e32 v55, v83, v83
	v_mul_f32_e32 v26, v80, v80
	v_fmac_f32_e32 v28, v77, v77
	v_fmac_f32_e32 v55, v78, v78
	v_fmac_f32_e32 v26, v79, v79
	s_waitcnt lgkmcnt(1)
	v_mov_b32_e32 v41, v72
	v_mov_b32_e32 v72, v34
	v_mul_f32_e32 v4, v48, v18
	v_mul_f32_e32 v5, v49, v19
	v_mul_f32_e32 v6, v0, v20
	v_mul_f32_e32 v7, v51, v21
	v_cvt_pk_bf16_f32 v4, v4, v5
	v_cvt_pk_bf16_f32 v5, v6, v7
	v_mul_f32_e32 v8, v52, v36
	v_mul_f32_e32 v9, v53, v37
	v_mul_f32_e32 v18, v50, v38
	v_mul_f32_e32 v19, v54, v39
	global_store_dwordx2 v[2:3], v[4:5], off offset:16
	v_cvt_pk_bf16_f32 v4, v8, v9
	v_cvt_pk_bf16_f32 v5, v18, v19
	global_store_dwordx2 v[2:3], v[4:5], off offset:80
	s_waitcnt vmcnt(6)
	v_mov_b32_e32 v4, v116
	v_mov_b32_e32 v5, v117
	v_mov_b32_e32 v6, v118
	v_mov_b32_e32 v7, v119
	s_nop 0
	v_mov_b32_e32 v18, v120
	v_mov_b32_e32 v19, v121
	v_mov_b32_e32 v20, v122
	v_mov_b32_e32 v21, v123
	v_mov_b32_e32 v9, v60
	v_mov_b32_e32 v8, v34
	v_mov_b32_e32 v60, v34
	v_pk_mul_f32 v[8:9], v[46:47], v[8:9]
	v_mov_b32_e32 v46, v27
	v_mul_f32_e32 v27, v76, v44
	v_add_f32_e32 v44, v8, v9
	v_pk_mul_f32 v[8:9], v[46:47], v[60:61]
	v_mov_b32_e32 v46, v12
	v_add_f32_e32 v12, v8, v9
	v_pk_mul_f32 v[8:9], v[46:47], v[22:23]
	v_mov_b32_e32 v46, v29
	v_mul_f32_e32 v22, v76, v12
	v_add_f32_e32 v12, v8, v9
	v_pk_mul_f32 v[8:9], v[46:47], v[34:35]
	v_mov_b32_e32 v46, v10
	v_add_f32_e32 v10, v8, v9
	v_pk_mul_f32 v[8:9], v[46:47], v[24:25]
	v_mov_b32_e32 v46, v11
	v_mov_b32_e32 v35, v71
	v_mul_f32_e32 v24, v76, v10
	v_add_f32_e32 v10, v8, v9
	v_pk_mul_f32 v[8:9], v[46:47], v[68:69]
	v_mov_b32_e32 v46, v13
	v_mul_f32_e32 v44, v76, v44
	v_mul_f32_e32 v25, v76, v10
	v_add_f32_e32 v10, v8, v9
	v_pk_mul_f32 v[8:9], v[46:47], v[34:35]
	v_mul_f32_e32 v23, v76, v12
	v_add_f32_e32 v8, v8, v9
	v_mul_f32_e32 v29, v76, v10
	v_mul_f32_e32 v45, v76, v8
	v_mul_f32_e32 v50, v50, v50
	v_fmac_f32_e32 v50, v0, v0
	v_mul_f32_e32 v0, v54, v54
	v_mov_b32_e32 v35, v42
	v_mov_b32_e32 v46, v32
	v_mov_b32_e32 v37, v64
	v_mov_b32_e32 v36, v34
	v_fmac_f32_e32 v0, v51, v51
	v_mov_b32_e32 v64, v34
	s_waitcnt lgkmcnt(0)
	v_mov_b32_e32 v39, v74
	v_mov_b32_e32 v38, v34
	v_mul_f32_e32 v4, v44, v4
	v_mul_f32_e32 v5, v22, v5
	v_mul_f32_e32 v6, v27, v6
	v_mul_f32_e32 v7, v24, v7
	v_cvt_pk_bf16_f32 v4, v4, v5
	v_cvt_pk_bf16_f32 v5, v6, v7
	v_mul_f32_e32 v8, v25, v18
	v_mul_f32_e32 v9, v29, v19
	v_mul_f32_e32 v10, v23, v20
	v_mul_f32_e32 v11, v45, v21
	global_store_dwordx2 v[2:3], v[4:5], off offset:32
	v_cvt_pk_bf16_f32 v4, v8, v9
	v_cvt_pk_bf16_f32 v5, v10, v11
	global_store_dwordx2 v[2:3], v[4:5], off offset:96
	s_waitcnt vmcnt(6)
	v_mov_b32_e32 v6, v124
	v_mov_b32_e32 v7, v125
	v_mov_b32_e32 v8, v126
	v_mov_b32_e32 v9, v127
	v_mov_b32_e32 v10, v128
	v_mov_b32_e32 v11, v129
	v_mov_b32_e32 v12, v130
	v_mov_b32_e32 v13, v131
	v_add_f32_e32 v18, v28, v55
	v_mul_f32_e32 v4, v52, v52
	v_add_f32_e32 v18, v18, v26
	v_mul_f32_e32 v5, v53, v53
	v_fmac_f32_e32 v4, v48, v48
	v_add_f32_e32 v18, v18, v56
	v_fmac_f32_e32 v5, v49, v49
	v_add_f32_e32 v4, v18, v4
	v_add_f32_e32 v4, v4, v5
	v_add_f32_e32 v19, v4, v50
	v_mul_f32_e32 v20, v25, v25
	v_pk_mul_f32 v[4:5], v[46:47], v[34:35]
	v_mov_b32_e32 v46, v30
	v_add_f32_e32 v0, v19, v0
	v_fmac_f32_e32 v20, v44, v44
	v_mul_f32_e32 v19, v29, v29
	v_add_f32_e32 v21, v4, v5
	v_pk_mul_f32 v[4:5], v[46:47], v[36:37]
	v_mov_b32_e32 v46, v31
	v_mul_f32_e32 v18, v23, v23
	v_add_f32_e32 v0, v0, v20
	v_fmac_f32_e32 v19, v22, v22
	v_add_f32_e32 v22, v4, v5
	v_pk_mul_f32 v[4:5], v[46:47], v[64:65]
	v_mov_b32_e32 v46, v16
	v_fmac_f32_e32 v18, v27, v27
	v_mov_b32_e32 v35, v43
	v_add_f32_e32 v0, v0, v19
	v_add_f32_e32 v19, v4, v5
	v_pk_mul_f32 v[4:5], v[46:47], v[38:39]
	v_mov_b32_e32 v46, v33
	v_mul_f32_e32 v20, v45, v45
	v_add_f32_e32 v0, v0, v18
	v_mul_f32_e32 v18, v76, v19
	v_add_f32_e32 v19, v4, v5
	v_pk_mul_f32 v[4:5], v[46:47], v[34:35]
	v_mov_b32_e32 v46, v14
	v_fmac_f32_e32 v20, v24, v24
	v_mul_f32_e32 v14, v76, v19
	v_add_f32_e32 v19, v4, v5
	v_pk_mul_f32 v[4:5], v[46:47], v[40:41]
	v_mov_b32_e32 v46, v15
	v_add_f32_e32 v0, v0, v20
	v_add_f32_e32 v20, v4, v5
	v_pk_mul_f32 v[4:5], v[46:47], v[72:73]
	v_mov_b32_e32 v35, v75
	v_mov_b32_e32 v46, v17
	v_mul_f32_e32 v17, v76, v20
	v_add_f32_e32 v20, v4, v5
	v_mul_f32_e32 v16, v76, v22
	v_pk_mul_f32 v[4:5], v[46:47], v[34:35]
	v_mul_f32_e32 v22, v17, v17
	v_mul_f32_e32 v20, v76, v20
	v_add_f32_e32 v4, v4, v5
	v_fmac_f32_e32 v22, v16, v16
	v_mul_f32_e32 v5, v20, v20
	v_mul_f32_e32 v21, v76, v21
	v_mul_f32_e32 v15, v14, v14
	v_mul_f32_e32 v23, v76, v4
	v_add_f32_e32 v0, v0, v22
	v_fmac_f32_e32 v5, v18, v18
	v_mul_f32_e32 v19, v76, v19
	v_fmac_f32_e32 v15, v21, v21
	v_mul_f32_e32 v4, v23, v23
	v_add_f32_e32 v0, v0, v5
	v_fmac_f32_e32 v4, v19, v19
	v_add_f32_e32 v0, v0, v15
	v_add_f32_e32 v0, v0, v4
	ds_bpermute_b32 v4, v149, v0
	v_mul_f32_e32 v5, v16, v6
	v_mul_f32_e32 v6, v18, v7
	v_mul_f32_e32 v7, v21, v8
	v_mul_f32_e32 v8, v19, v9
	v_cvt_pk_bf16_f32 v6, v5, v6
	v_cvt_pk_bf16_f32 v7, v7, v8
	v_mul_f32_e32 v9, v17, v10
	v_mul_f32_e32 v10, v20, v11
	v_mul_f32_e32 v11, v14, v12
	v_mul_f32_e32 v12, v23, v13
	global_store_dwordx2 v[2:3], v[6:7], off offset:48
	v_cvt_pk_bf16_f32 v6, v9, v10
	v_cvt_pk_bf16_f32 v7, v11, v12
	global_store_dwordx2 v[2:3], v[6:7], off offset:112
	s_and_b64 exec, exec, s[0:1]
	s_cbranch_execz .LBB0_929
	v_lshlrev_b64 v[2:3], 5, v[178:179]
	v_lshl_add_u64 v[2:3], s[20:21], 0, v[2:3]
	s_lshl_b32 s10, s47, 2
	v_lshl_add_u64 v[2:3], v[2:3], 0, s[10:11]
	s_waitcnt lgkmcnt(0)
	v_add_f32_e32 v0, v0, v4
	global_store_dword v[2:3], v0, off
	s_branch .LBB0_929
